# baseline (speedup 1.0000x reference)
; #define PG8_STAGE(bufoff, gbase, voff) do { _Pragma("unroll") for (int _i = 0; _i < 2; ++_i) \
;         __builtin_amdgcn_global_load_lds((const unsigned*)((const char*)(gbase) + (voff)[_i]), (LAS unsigned*)(lds + (bufoff) + ldsw + _i * 8192), 16, 0, 0); } while (0)
; #define PG8_BAR __builtin_amdgcn_s_barrier()
; __device__ __forceinline__ void gemm_phase(LAS unsigned char* lds, const GemmD& g) {
;     ...
;     for (int i = 0; i < 2; ++i) { int R, C; stage_rc(tid * 16 + i * 8192, R, C); const int Rb = perm ? ((R & ~31) + perm32(R & 31)) : R;
;         voffA[i] = (unsigned)(R * K + C) * 2u; voffB[i] = (unsigned)(Rb * K + C) * 2u; }
;     const size_t kstep = (size_t)(BK * 2);
;     const size_t hstep = (size_t)HALF * K * 2;
;     const size_t tstep = 2 * hstep;
;     const unsigned ldsw = (unsigned)wid * 1024u;
;     const int aoff = lds_byte(wr * 64 + fr, fq * 8), boff = lds_byte(wc * 32 + fr, fq * 8);
;     ...
;     Unit cur, nxt; int ui = 0;
;     if (!unit_get(g, nM, nN, G, cblk, 0, cur)) return;
;     f32x4 acc[2][2][4][2];
; #pragma unroll
;     for (int a = 0; a < 2; ++a)
; #pragma unroll
;         for (int b = 0; b < 2; ++b)
; #pragma unroll
;             for (int m = 0; m < 4; ++m)
; #pragma unroll
;                 for (int n = 0; n < 2; ++n) acc[a][b][m][n] = (f32x4){0.f, 0.f, 0.f, 0.f};
;     bf16x8 At[4][2], B0[2][2], B1[2][2];
;     const char* cA = (const char*)g.A + (size_t)cur.pm * tstep + (size_t)cur.k0 * kstep; const char* cB = (const char*)g.Bt + (size_t)cur.pn * tstep + (size_t)cur.k0 * kstep;
;     PG8_STAGE(PG8_SB(0, 0), cB, voffB); PG8_STAGE(PG8_SA(0, 0), cA, voffA); PG8_STAGE(PG8_SB(0, 1), cB + hstep, voffB); PG8_STAGE(PG8_SA(0, 1), cA + hstep, voffA);
;     if (wr == 1) PG8_BAR;
.LBB0_123:
	s_and_b64 vcc, exec, s[2:3]
	s_cbranch_vccz .LBB0_60
	v_lshlrev_b32_e32 v13, 6, v13
	v_sub_u32_e32 v12, v12, v13
	v_lshlrev_b32_e32 v10, 5, v10
	v_ashrrev_i16_sdwa v12, v213, sext(v12) dst_sel:DWORD dst_unused:UNUSED_PAD src0_sel:DWORD src1_sel:BYTE_0
	v_and_b32_e32 v10, 32, v10
	v_bfe_i32 v12, v12, 0, 16
	v_add_u32_e32 v13, v10, v12
	v_mul_lo_u32 v11, v11, s0
	v_mul_lo_u32 v14, v14, s0
	v_lshlrev_b32_e32 v2, 5, v2
	v_add_lshl_u32 v166, v13, v11, 1
	v_add_lshl_u32 v168, v14, v13, 1
	v_and_b32_e32 v13, 32, v2
	v_lshlrev_b32_e32 v2, 6, v7
	v_sub_u32_e32 v2, v3, v2
	v_ashrrev_i16_sdwa v2, v213, sext(v2) dst_sel:DWORD dst_unused:UNUSED_PAD src0_sel:DWORD src1_sel:BYTE_0
	s_mov_b32 s1, s34
	v_bfe_i32 v14, v2, 0, 16
	s_lshl_b64 s[72:73], s[0:1], 8
	s_lshl_b64 s[58:59], s[0:1], 9
	v_add_u32_e32 v2, v13, v14
	v_mul_lo_u32 v15, v6, s0
	v_mul_lo_u32 v3, v9, s0
	s_ashr_i32 s1, s56, 31
	v_add_lshl_u32 v170, v2, v15, 1
	v_add_lshl_u32 v172, v3, v2, 1
	s_mul_i32 s1, s58, s1
	s_mul_hi_u32 s2, s58, s56
	v_ashrrev_i32_e32 v2, 31, v1
	s_add_i32 s1, s2, s1
	s_lshr_b32 s2, s0, 23
	v_mul_lo_u32 v2, s58, v2
	v_mul_hi_u32 v3, s58, v1
	s_ashr_i32 s6, s33, 6
	s_mul_i32 s0, s2, s56
	v_add_u32_e32 v2, v3, v2
	v_mul_lo_u32 v3, s2, v1
	s_ashr_i32 s7, s33, 8
	s_lshl_b32 s87, s6, 10
	s_add_i32 s1, s1, s0
	s_mul_i32 s0, s58, s56
	v_add_u32_e32 v3, v2, v3
	v_mul_lo_u32 v2, s58, v1
	s_add_u32 s0, s18, s0
	v_lshl_add_u64 v[2:3], s[92:93], 0, v[2:3]
	s_addc_u32 s1, s19, s1
	v_lshl_add_u64 v[2:3], v[2:3], 0, v[4:5]
	s_add_i32 s2, s87, 0
	s_add_i32 m0, s2, 0x10000
	v_readfirstlane_b32 s8, v2
	v_readfirstlane_b32 s9, v3
	v_lshl_add_u64 v[4:5], s[0:1], 0, v[4:5]
	s_add_i32 s3, s2, 0x2000
	v_readfirstlane_b32 s0, v4
	v_readfirstlane_b32 s1, v5
	v_lshl_add_u64 v[6:7], v[2:3], 0, s[72:73]
	global_load_lds_dwordx4 v172, s[8:9]
	s_add_i32 m0, s2, 0x12000
	v_lshl_add_u64 v[16:17], v[4:5], 0, s[72:73]
	global_load_lds_dwordx4 v168, s[8:9]
	s_mov_b32 m0, s2
	s_add_i32 s64, s2, 0x4000
	global_load_lds_dwordx4 v170, s[0:1]
	s_mov_b32 m0, s3
	s_add_i32 s65, s2, 0x6000
	global_load_lds_dwordx4 v166, s[0:1]
	s_add_i32 m0, s2, 0x14000
	v_readfirstlane_b32 s0, v6
	v_readfirstlane_b32 s1, v7
	v_writelane_b32 v255, s28, 27
	s_nop 1
	v_writelane_b32 v255, s29, 28
	v_writelane_b32 v255, s33, 29
	global_load_lds_dwordx4 v172, s[0:1]
	s_add_i32 m0, s2, 0x16000
	s_cmp_lg_u32 s7, 1
	global_load_lds_dwordx4 v168, s[0:1]
	v_readfirstlane_b32 s0, v16
	v_readfirstlane_b32 s1, v17
	s_mov_b32 m0, s64
	s_nop 3
	global_load_lds_dwordx4 v170, s[0:1]
	s_mov_b32 m0, s65
	s_nop 0
	global_load_lds_dwordx4 v166, s[0:1]
	s_setprio 1
	s_cbranch_scc1 .LBB0_126
	s_setprio 0
	s_barrier
